# attention step row-max chain: four s_nop 0 and two self-max canonicalisations dropped
# speedup vs baseline: 1.0007x; 1.0007x over previous
.LBB0_283:
	v_max3_f32 v130, v80, v64, v81
	v_max3_f32 v131, v65, v82, v66
	s_cmp_lg_u32 s49, 0
	v_max3_f32 v130, v130, v83, v67
	v_max3_f32 v131, v131, v84, v68
	s_cselect_b64 s[72:73], -1, 0
	v_max3_f32 v130, v130, v85, v69
	v_max3_f32 v131, v131, v86, v70
	s_cmp_eq_u32 s49, 0
	v_max3_f32 v130, v130, v87, v71
	v_max3_f32 v131, v131, v88, v72
	v_max3_f32 v130, v130, v89, v73
	v_max3_f32 v131, v131, v90, v74
	v_max3_f32 v130, v130, v91, v75
	v_max3_f32 v131, v131, v92, v76
	v_max3_f32 v130, v130, v93, v77
	v_max3_f32 v131, v131, v94, v78
	v_max3_f32 v130, v130, v95, v79
	v_max_f32_e32 v130, v130, v131
	v_mov_b32_e32 v131, v130
	s_nop 1
	v_permlane32_swap_b32_e32 v130, v131
	v_max_f32_e32 v130, v130, v131
	s_cbranch_scc1 .LBB0_286
	s_mov_b32 s52, 0x42c00000
	v_cmp_lt_f32_e32 vcc, s52, v130
	s_cbranch_vccz .LBB0_287
	v_max_f32_e32 v130, v130, v130
	v_max_f32_e32 v130, 0, v130
